# cross-attention staging: K/V tiles loaded HBM to LDS directly (global_load_lds_dwordx4, m0 per group) instead of VGPR round trip plus ds_write
# baseline (speedup 1.0000x reference)
; __device__ __forceinline__ void xattn_phase(const bf16* QXB, const bf16* MKF, const bf16* MVF, bf16* OXB, int G, int tid) {
;     ...
;     for (int it = (int)blockIdx.x * (MK_THREADS / 64) + wave; it < NIT; it += G * (MK_THREADS / 64)) { const int qb = it % NQ32, bhx = it / NQ32, h = bhx % XH, b = bhx / XH;
;         const size_t row0 = (size_t)b * SEQ + 32 * qb;
;         const bf16* qp = QXB + (row0 + r32) * XW + h * XHD + 8 * hh; const bf16* kp = MKF + (size_t)(b * XH + h) * 32768 + lane * 8;
;         bf16x8 qf[8];
; #pragma unroll
;         for (int ks = 0; ks < 8; ++ks) qf[ks] = *(const bf16x8*)(qp + 16 * ks);
;         const bf16* vp = MVF + (size_t)(b * XH + h) * 32768 + lane * 16;
;         f32x16 o[4]; o[0] = f32x16{}; o[1] = f32x16{}; o[2] = f32x16{}; o[3] = f32x16{}; float m_run = -INFINITY, l_run = 0.f;
;     ...
;         bf16x8 kfa[8], kfb[8];
; #pragma unroll
;         for (int ks = 0; ks < 8; ++ks) kfa[ks] = *(const bf16x8*)(kp + ks * 512);
.LBB0_1511:
	s_ashr_i32 s0, s8, 31
	s_lshr_b32 s1, s0, 25
	s_add_i32 s1, s8, s1
	s_ashr_i32 s2, s1, 7
	s_and_b32 s1, s1, 0x7ffff80
	s_sub_i32 s6, s8, s1
	s_lshr_b32 s1, s2, 30
	s_add_i32 s1, s2, s1
	s_lshr_b32 s0, s0, 23
	s_and_b32 s1, s1, -4
	s_add_i32 s0, s8, s0
	s_sub_i32 s7, s2, s1
	s_ashr_i32 s2, s0, 9
	s_ashr_i32 s3, s2, 31
	s_lshl_b64 s[0:1], s[2:3], 12
	s_lshl_b32 s3, s6, 5
	s_ashr_i32 s6, s3, 31
	s_add_u32 s0, s0, s3
	s_addc_u32 s1, s1, s6
	v_mov_b32_e32 v3, s1
	v_or_b32_e32 v2, s0, v222
	v_readlane_b32 s0, v252, 19
	v_lshlrev_b64 v[4:5], 10, v[2:3]
	v_readlane_b32 s1, v252, 20
	s_lshl_b32 s2, s2, 2
	s_add_i32 s2, s2, s7
	v_lshl_add_u64 v[4:5], s[0:1], 0, v[4:5]
	s_lshl_b32 s0, s7, 7
	s_ashr_i32 s1, s0, 31
	v_lshl_add_u64 v[4:5], s[0:1], 1, v[4:5]
	v_lshl_add_u64 v[4:5], v[4:5], 0, v[214:215]
	s_ashr_i32 s3, s2, 31
	global_load_dwordx4 v[82:85], v[4:5], off
	global_load_dwordx4 v[86:89], v[4:5], off offset:32
	global_load_dwordx4 v[90:93], v[4:5], off offset:64
	global_load_dwordx4 v[94:97], v[4:5], off offset:96
	global_load_dwordx4 v[98:101], v[4:5], off offset:128
	global_load_dwordx4 v[102:105], v[4:5], off offset:160
	global_load_dwordx4 v[106:109], v[4:5], off offset:192
	global_load_dwordx4 v[110:113], v[4:5], off offset:224
	s_lshl_b64 s[2:3], s[2:3], 16
	v_lshl_add_u64 v[182:183], v[226:227], 0, s[2:3]
	v_mov_b32_e32 v50, v215
	v_mov_b32_e32 v51, v215
	v_lshlrev_b64 v[232:233], 9, v[2:3]
	s_add_u32 s2, s9, s2
	v_mov_b32_e32 v52, v215
	v_mov_b32_e32 v53, v215
	v_mov_b32_e32 v54, v215
	v_mov_b32_e32 v55, v215
	v_mov_b32_e32 v56, v215
	v_mov_b32_e32 v57, v215
	v_mov_b32_e32 v58, v215
	v_mov_b32_e32 v59, v215
	v_mov_b32_e32 v60, v215
	v_mov_b32_e32 v61, v215
	v_mov_b32_e32 v62, v215
	v_mov_b32_e32 v63, v215
	v_mov_b32_e32 v64, v215
	v_mov_b32_e32 v65, v215
	v_mov_b64_e32 v[34:35], v[50:51]
	v_mov_b64_e32 v[18:19], v[50:51]
	v_mov_b64_e32 v[2:3], v[50:51]
	s_mov_b32 s11, 0
	s_addc_u32 s3, s10, s3
	v_mov_b32_e32 v231, 0
	v_mov_b32_e32 v248, 0xff800000
	v_mov_b64_e32 v[36:37], v[52:53]
	v_mov_b64_e32 v[38:39], v[54:55]
	v_mov_b64_e32 v[40:41], v[56:57]
	v_mov_b64_e32 v[42:43], v[58:59]
	v_mov_b64_e32 v[44:45], v[60:61]
	v_mov_b64_e32 v[46:47], v[62:63]
	v_mov_b64_e32 v[48:49], v[64:65]
	v_mov_b64_e32 v[20:21], v[52:53]
	v_mov_b64_e32 v[22:23], v[54:55]
	v_mov_b64_e32 v[24:25], v[56:57]
	v_mov_b64_e32 v[26:27], v[58:59]
	v_mov_b64_e32 v[28:29], v[60:61]
	v_mov_b64_e32 v[30:31], v[62:63]
	v_mov_b64_e32 v[32:33], v[64:65]
	v_mov_b64_e32 v[4:5], v[52:53]
	v_mov_b64_e32 v[6:7], v[54:55]
	v_mov_b64_e32 v[8:9], v[56:57]
	v_mov_b64_e32 v[10:11], v[58:59]
	v_mov_b64_e32 v[12:13], v[60:61]
	v_mov_b64_e32 v[14:15], v[62:63]
	v_mov_b64_e32 v[16:17], v[64:65]
	s_and_b32 s6, s8, 7
	s_lshl_b32 s6, s6, 13
	s_mov_b32 s7, 0
	v_lshl_add_u64 v[182:183], s[6:7], 0, v[182:183]
	v_add_co_u32_e32 v184, vcc, 0x1000, v182
	s_nop 1
	v_addc_co_u32_e32 v185, vcc, 0, v183, vcc
	v_lshl_add_u64 v[186:187], s[6:7], 0, v[228:229]
	v_lshl_add_u64 v[186:187], s[2:3], 0, v[186:187]
	v_add_co_u32_e32 v186, vcc, 0x22a00000, v186
	s_nop 1
	v_addc_co_u32_e32 v187, vcc, 0, v187, vcc
	v_add_co_u32_e32 v188, vcc, 0x1000, v186
	s_nop 1
	v_addc_co_u32_e32 v189, vcc, 0, v187, vcc
	s_mov_b32 m0, s6
	s_nop 0
	global_load_lds_dwordx4 v[182:183], off
	global_load_lds_dwordx4 v[182:183], off offset:1024
	global_load_lds_dwordx4 v[182:183], off offset:2048
	global_load_lds_dwordx4 v[182:183], off offset:3072
	s_add_i32 m0, s6, 0x1000
	s_nop 0
	global_load_lds_dwordx4 v[184:185], off
	global_load_lds_dwordx4 v[184:185], off offset:1024
	global_load_lds_dwordx4 v[184:185], off offset:2048
	global_load_lds_dwordx4 v[184:185], off offset:3072
	s_add_i32 m0, s6, 0x10000
	s_nop 0
	global_load_lds_dwordx4 v[186:187], off
	s_add_i32 m0, s6, 0x103f0
	s_nop 0
	global_load_lds_dwordx4 v[186:187], off offset:16
	s_add_i32 m0, s6, 0x10000
	s_nop 0
	global_load_lds_dwordx4 v[186:187], off offset:2048
	s_add_i32 m0, s6, 0x103f0
	s_nop 0
	global_load_lds_dwordx4 v[186:187], off offset:2064
	s_add_i32 m0, s6, 0x11000
	s_nop 0
	global_load_lds_dwordx4 v[188:189], off
	s_add_i32 m0, s6, 0x113f0
	s_nop 0
	global_load_lds_dwordx4 v[188:189], off offset:16
	s_add_i32 m0, s6, 0x11000
	s_nop 0
	global_load_lds_dwordx4 v[188:189], off offset:2048
	s_add_i32 m0, s6, 0x113f0
	s_nop 0
	global_load_lds_dwordx4 v[188:189], off offset:2064
	v_mov_b32_e32 v180, v224
	v_add_u32_e32 v181, 0x10000, v224
	s_waitcnt vmcnt(0)
	s_barrier
	ds_read_b128 v[114:117], v180
	ds_read_b128 v[118:121], v180 offset:1024
	ds_read_b128 v[122:125], v180 offset:2048
	ds_read_b128 v[126:129], v180 offset:3072
	ds_read_b128 v[130:133], v180 offset:4096
	ds_read_b128 v[134:137], v180 offset:5120
	ds_read_b128 v[138:141], v180 offset:6144
	ds_read_b128 v[142:145], v180 offset:7168
